# m2b + final RMSNorm row loop software-pipelined (next rows' loads in flight during scale/store, gains hoisted)
# baseline (speedup 1.0000x reference)
; __device__ __forceinline__ float rstd_of(const unsigned long long* ssq, int row) { return rsqrtf((float)ssq[row] * (1.0f / (SSQ_SCALE * 1024.0f)) + EPS); }
; __global__ void __launch_bounds__(512, 2) mk_fwd(Args a) {
;     ...
;     if (IN(8)) {
;         const float* gf = a.in[22];
;         for (int orow0 = gw * 4; orow0 < NOUT_ROWS; orow0 += NGW * 4) {
;             u32x4 hv[4][2]; float rs[4];
; #pragma unroll
;             for (int i = 0; i < 4; ++i) { const int row = orow0 + i;
;                 rs[i] = rstd_of(SSQ3, row);
; #pragma unroll
;                 for (int j = 0; j < 2; ++j) hv[i][j] = *(const u32x4*)(H + (size_t)row * D + (j * 64 + lane) * 8); }
; #pragma unroll
;             for (int j = 0; j < 2; ++j) { const int col = (j * 64 + lane) * 8; const f32x4 g0 = *(const f32x4*)(gf + col), g1 = *(const f32x4*)(gf + col + 4);
; #pragma unroll
.LBB0_712:
	s_cmp_lt_i32 s30, 9
	s_cselect_b64 s[2:3], -1, 0
	s_cmp_gt_i32 s31, 8
	v_readlane_b32 s8, v254, 0
	s_cselect_b64 s[4:5], -1, 0
	s_cmpk_lt_i32 s8, 0x6000
	s_cselect_b64 s[6:7], -1, 0
	s_and_b64 s[2:3], s[2:3], s[6:7]
	s_and_b64 s[2:3], s[2:3], s[4:5]
	s_and_b64 vcc, exec, s[2:3]
	s_cbranch_vccz .LBB0_715
	s_load_dwordx4 s[12:15], s[0:1], 0xb0
	s_lshl_b32 s6, s8, 2
	s_ashr_i32 s7, s6, 31
	v_lshlrev_b32_e32 v24, 5, v203
	v_mov_b32_e32 v25, 0
	s_ashr_i32 s45, s44, 31
	s_lshl_b64 s[0:1], s[6:7], 11
	v_and_b32_e32 v0, 63, v202
	s_waitcnt lgkmcnt(0)
	v_lshl_add_u64 v[26:27], s[12:13], 0, v[24:25]
	s_lshl_b64 s[8:9], s[6:7], 3
	s_lshl_b64 s[10:11], s[44:45], 3
	v_lshl_or_b32 v48, v0, 4, s0
	v_mov_b32_e32 v49, s1
	s_lshl_b64 s[12:13], s[44:45], 11
	s_lshl_b64 s[0:1], s[6:7], 12
	s_add_u32 s0, s14, s0
	v_lshlrev_b32_e32 v24, 5, v0
	s_addc_u32 s1, s15, s1
	v_lshl_add_u64 v[50:51], s[0:1], 0, v[24:25]
	s_lshl_b64 s[14:15], s[44:45], 12
	v_mov_b32_e32 v68, 0x358637bd
	s_mov_b32 s7, 0x800000
	s_add_u32 s16, s28, 0x3200000
	s_addc_u32 s17, s29, 0
	v_lshl_add_u64 v[48:49], s[16:17], 0, v[48:49]
	s_add_u32 s0, s28, s8
	s_addc_u32 s1, s29, s9
	s_add_u32 s0, s0, 0x400000
	s_addc_u32 s1, s1, 0
	global_load_dwordx4 v[88:91], v[26:27], off
	global_load_dwordx4 v[92:95], v[26:27], off offset:16
	global_load_dwordx4 v[96:99], v[26:27], off offset:2048
	global_load_dwordx4 v[100:103], v[26:27], off offset:2064
	v_add_co_u32_e32 v52, vcc, 0x1000, v48
	s_nop 1
	v_addc_co_u32_e32 v53, vcc, 0, v49, vcc
	global_load_dwordx4 v[136:139], v25, s[0:1]
	global_load_dwordx4 v[140:143], v25, s[0:1] offset:16
	global_load_dwordx4 v[104:107], v[48:49], off
	global_load_dwordx4 v[108:111], v[48:49], off offset:1024
	global_load_dwordx4 v[112:115], v[48:49], off offset:2048
	global_load_dwordx4 v[116:119], v[48:49], off offset:3072
	global_load_dwordx4 v[120:123], v[52:53], off
	global_load_dwordx4 v[124:127], v[52:53], off offset:1024
	global_load_dwordx4 v[128:131], v[52:53], off offset:2048
	global_load_dwordx4 v[132:135], v[52:53], off offset:3072
	s_waitcnt vmcnt(0)
	s_branch .Lp8_entry
.Lp8_top:
	s_waitcnt vmcnt(16)
.Lp8_entry:
	v_mov_b64_e32 v[144:145], v[104:105]
	v_mov_b64_e32 v[146:147], v[106:107]
	v_mov_b64_e32 v[148:149], v[108:109]
	v_mov_b64_e32 v[150:151], v[110:111]
	v_mov_b64_e32 v[152:153], v[112:113]
	v_mov_b64_e32 v[154:155], v[114:115]
	v_mov_b64_e32 v[156:157], v[116:117]
	v_mov_b64_e32 v[158:159], v[118:119]
	v_mov_b64_e32 v[160:161], v[120:121]
	v_mov_b64_e32 v[162:163], v[122:123]
	v_mov_b64_e32 v[164:165], v[124:125]
	v_mov_b64_e32 v[166:167], v[126:127]
	v_mov_b64_e32 v[168:169], v[128:129]
	v_mov_b64_e32 v[170:171], v[130:131]
	v_mov_b64_e32 v[172:173], v[132:133]
	v_mov_b64_e32 v[174:175], v[134:135]
	v_mov_b64_e32 v[176:177], v[136:137]
	v_mov_b64_e32 v[178:179], v[138:139]
	v_mov_b64_e32 v[180:181], v[140:141]
	v_mov_b64_e32 v[182:183], v[142:143]
	s_add_i32 s6, s6, s44
	s_add_u32 s0, s0, s10
	s_addc_u32 s1, s1, s11
	v_lshl_add_u64 v[48:49], v[48:49], 0, s[12:13]
	s_cmp_lt_i32 s6, 0x18000
	s_cbranch_scc0 .Lp8_noload
	v_add_co_u32_e32 v52, vcc, 0x1000, v48
	s_nop 1
	v_addc_co_u32_e32 v53, vcc, 0, v49, vcc
	global_load_dwordx4 v[136:139], v25, s[0:1]
	global_load_dwordx4 v[140:143], v25, s[0:1] offset:16
	global_load_dwordx4 v[104:107], v[48:49], off
	global_load_dwordx4 v[108:111], v[48:49], off offset:1024
	global_load_dwordx4 v[112:115], v[48:49], off offset:2048
	global_load_dwordx4 v[116:119], v[48:49], off offset:3072
	global_load_dwordx4 v[120:123], v[52:53], off
	global_load_dwordx4 v[124:127], v[52:53], off offset:1024
	global_load_dwordx4 v[128:131], v[52:53], off offset:2048
	global_load_dwordx4 v[132:135], v[52:53], off offset:3072
.Lp8_noload:
	v_add_co_u32_e32 v54, vcc, 0x1000, v50
	s_nop 1
	v_addc_co_u32_e32 v55, vcc, 0, v51, vcc
	v_add_co_u32_e32 v56, vcc, 0x2000, v50
	s_nop 1
	v_addc_co_u32_e32 v57, vcc, 0, v51, vcc
	v_add_co_u32_e32 v58, vcc, 0x3000, v50
	s_nop 1
	v_addc_co_u32_e32 v59, vcc, 0, v51, vcc
	v_ffbh_u32_e32 v0, v177
	v_ffbh_u32_e32 v4, v179
	v_min_u32_e32 v2, 32, v0
	v_min_u32_e32 v6, 32, v4
	v_lshlrev_b64 v[0:1], v2, v[176:177]
	v_lshlrev_b64 v[4:5], v6, v[178:179]
	v_min_u32_e32 v0, 1, v0
	v_min_u32_e32 v4, 1, v4
	v_or_b32_e32 v0, v1, v0
	v_or_b32_e32 v4, v5, v4
	v_cvt_f32_u32_e32 v0, v0
	v_cvt_f32_u32_e32 v4, v4
	v_sub_u32_e32 v1, 32, v2
	v_sub_u32_e32 v5, 32, v6
	v_ldexp_f32 v0, v0, v1
	v_ldexp_f32 v4, v4, v5
	v_fmamk_f32 v0, v0, 0x30800000, v68
	v_fmamk_f32 v4, v4, 0x30800000, v68
	v_mul_f32_e32 v1, 0x4b800000, v0
	v_mul_f32_e32 v5, 0x4b800000, v4
	v_cmp_gt_f32_e32 vcc, s7, v0
	v_cmp_gt_f32_e64 s[2:3], s7, v4
	s_nop 0
	v_cndmask_b32_e32 v0, v0, v1, vcc
	v_cndmask_b32_e64 v4, v4, v5, s[2:3]
	v_rsq_f32_e32 v0, v0
	v_rsq_f32_e32 v4, v4
	v_mul_f32_e32 v1, 0x45800000, v0
	v_mul_f32_e32 v5, 0x45800000, v4
	v_cndmask_b32_e32 v60, v0, v1, vcc
	v_cndmask_b32_e64 v62, v4, v5, s[2:3]
	v_ffbh_u32_e32 v0, v181
	v_ffbh_u32_e32 v4, v183
	v_min_u32_e32 v2, 32, v0
	v_min_u32_e32 v6, 32, v4
	v_lshlrev_b64 v[0:1], v2, v[180:181]
	v_lshlrev_b64 v[4:5], v6, v[182:183]
	v_min_u32_e32 v0, 1, v0
	v_min_u32_e32 v4, 1, v4
	v_or_b32_e32 v0, v1, v0
	v_or_b32_e32 v4, v5, v4
	v_cvt_f32_u32_e32 v0, v0
	v_cvt_f32_u32_e32 v4, v4
	v_sub_u32_e32 v1, 32, v2
	v_sub_u32_e32 v5, 32, v6
	v_ldexp_f32 v0, v0, v1
	v_ldexp_f32 v4, v4, v5
	v_fmamk_f32 v0, v0, 0x30800000, v68
	v_fmamk_f32 v4, v4, 0x30800000, v68
	v_mul_f32_e32 v1, 0x4b800000, v0
	v_mul_f32_e32 v5, 0x4b800000, v4
	v_cmp_gt_f32_e32 vcc, s7, v0
	v_cmp_gt_f32_e64 s[2:3], s7, v4
	s_nop 0
	v_cndmask_b32_e32 v0, v0, v1, vcc
	v_cndmask_b32_e64 v4, v4, v5, s[2:3]
	v_rsq_f32_e32 v0, v0
; __device__ __forceinline__ float bf_lo(unsigned u) { return __uint_as_float(u << 16); }
; __device__ __forceinline__ float bf_hi(unsigned u) { return __uint_as_float(u & 0xffff0000u); }
; __global__ void __launch_bounds__(512, 2) mk_fwd(Args a) {
;     ...
;             for (int j = 0; j < 2; ++j) { const int col = (j * 64 + lane) * 8; const f32x4 g0 = *(const f32x4*)(gf + col), g1 = *(const f32x4*)(gf + col + 4);
; #pragma unroll
;                 for (int i = 0; i < 4; ++i) { const u32x4 h4 = hv[i][j]; const float r = rs[i];
;                     f32x4 o0, o1; o0.x = bf_lo(h4.x) * r * g0.x; o0.y = bf_hi(h4.x) * r * g0.y; o0.z = bf_lo(h4.y) * r * g0.z; o0.w = bf_hi(h4.y) * r * g0.w;
;                     o1.x = bf_lo(h4.z) * r * g1.x; o1.y = bf_hi(h4.z) * r * g1.y; o1.z = bf_lo(h4.w) * r * g1.z; o1.w = bf_hi(h4.w) * r * g1.w;
;                     float* op = a.out + (size_t)(orow0 + i) * D + col; *(f32x4*)op = o0; *(f32x4*)(op + 4) = o1; } }
;         }
	v_rsq_f32_e32 v4, v4
	v_mul_f32_e32 v1, 0x45800000, v0
	v_mul_f32_e32 v5, 0x45800000, v4
	v_cndmask_b32_e32 v64, v0, v1, vcc
	v_cndmask_b32_e64 v66, v4, v5, s[2:3]
	v_lshlrev_b32_e32 v16, 16, v144
	v_and_b32_e32 v17, 0xffff0000, v144
	v_lshlrev_b32_e32 v18, 16, v145
	v_and_b32_e32 v19, 0xffff0000, v145
	v_lshlrev_b32_e32 v20, 16, v146
	v_and_b32_e32 v21, 0xffff0000, v146
	v_lshlrev_b32_e32 v22, 16, v147
	v_and_b32_e32 v23, 0xffff0000, v147
	v_pk_mul_f32 v[16:17], v[60:61], v[16:17] op_sel_hi:[0,1]
	v_pk_mul_f32 v[18:19], v[60:61], v[18:19] op_sel_hi:[0,1]
	v_pk_mul_f32 v[20:21], v[60:61], v[20:21] op_sel_hi:[0,1]
	v_pk_mul_f32 v[22:23], v[60:61], v[22:23] op_sel_hi:[0,1]
	v_pk_mul_f32 v[32:33], v[88:89], v[16:17]
	v_pk_mul_f32 v[34:35], v[90:91], v[18:19]
	v_pk_mul_f32 v[36:37], v[92:93], v[20:21]
	v_pk_mul_f32 v[38:39], v[94:95], v[22:23]
	global_store_dwordx4 v[50:51], v[32:35], off
	global_store_dwordx4 v[50:51], v[36:39], off offset:16
	v_lshlrev_b32_e32 v16, 16, v148
	v_and_b32_e32 v17, 0xffff0000, v148
	v_lshlrev_b32_e32 v18, 16, v149
	v_and_b32_e32 v19, 0xffff0000, v149
	v_lshlrev_b32_e32 v20, 16, v150
	v_and_b32_e32 v21, 0xffff0000, v150
	v_lshlrev_b32_e32 v22, 16, v151
	v_and_b32_e32 v23, 0xffff0000, v151
	v_pk_mul_f32 v[16:17], v[60:61], v[16:17] op_sel_hi:[0,1]
	v_pk_mul_f32 v[18:19], v[60:61], v[18:19] op_sel_hi:[0,1]
	v_pk_mul_f32 v[20:21], v[60:61], v[20:21] op_sel_hi:[0,1]
	v_pk_mul_f32 v[22:23], v[60:61], v[22:23] op_sel_hi:[0,1]
	v_pk_mul_f32 v[40:41], v[96:97], v[16:17]
	v_pk_mul_f32 v[42:43], v[98:99], v[18:19]
	v_pk_mul_f32 v[44:45], v[100:101], v[20:21]
	v_pk_mul_f32 v[46:47], v[102:103], v[22:23]
	global_store_dwordx4 v[50:51], v[40:43], off offset:2048
	global_store_dwordx4 v[50:51], v[44:47], off offset:2064
	v_lshlrev_b32_e32 v16, 16, v152
	v_and_b32_e32 v17, 0xffff0000, v152
	v_lshlrev_b32_e32 v18, 16, v153
	v_and_b32_e32 v19, 0xffff0000, v153
	v_lshlrev_b32_e32 v20, 16, v154
	v_and_b32_e32 v21, 0xffff0000, v154
	v_lshlrev_b32_e32 v22, 16, v155
	v_and_b32_e32 v23, 0xffff0000, v155
	v_pk_mul_f32 v[16:17], v[62:63], v[16:17] op_sel_hi:[0,1]
	v_pk_mul_f32 v[18:19], v[62:63], v[18:19] op_sel_hi:[0,1]
	v_pk_mul_f32 v[20:21], v[62:63], v[20:21] op_sel_hi:[0,1]
	v_pk_mul_f32 v[22:23], v[62:63], v[22:23] op_sel_hi:[0,1]
	v_pk_mul_f32 v[32:33], v[88:89], v[16:17]
	v_pk_mul_f32 v[34:35], v[90:91], v[18:19]
	v_pk_mul_f32 v[36:37], v[92:93], v[20:21]
	v_pk_mul_f32 v[38:39], v[94:95], v[22:23]
	global_store_dwordx4 v[54:55], v[32:35], off
	global_store_dwordx4 v[54:55], v[36:39], off offset:16
	v_lshlrev_b32_e32 v16, 16, v156
	v_and_b32_e32 v17, 0xffff0000, v156
	v_lshlrev_b32_e32 v18, 16, v157
	v_and_b32_e32 v19, 0xffff0000, v157
	v_lshlrev_b32_e32 v20, 16, v158
	v_and_b32_e32 v21, 0xffff0000, v158
	v_lshlrev_b32_e32 v22, 16, v159
	v_and_b32_e32 v23, 0xffff0000, v159
	v_pk_mul_f32 v[16:17], v[62:63], v[16:17] op_sel_hi:[0,1]
	v_pk_mul_f32 v[18:19], v[62:63], v[18:19] op_sel_hi:[0,1]
	v_pk_mul_f32 v[20:21], v[62:63], v[20:21] op_sel_hi:[0,1]
	v_pk_mul_f32 v[22:23], v[62:63], v[22:23] op_sel_hi:[0,1]
	v_pk_mul_f32 v[40:41], v[96:97], v[16:17]
	v_pk_mul_f32 v[42:43], v[98:99], v[18:19]
	v_pk_mul_f32 v[44:45], v[100:101], v[20:21]
	v_pk_mul_f32 v[46:47], v[102:103], v[22:23]
	global_store_dwordx4 v[54:55], v[40:43], off offset:2048
	global_store_dwordx4 v[54:55], v[44:47], off offset:2064
	v_lshlrev_b32_e32 v16, 16, v160
	v_and_b32_e32 v17, 0xffff0000, v160
	v_lshlrev_b32_e32 v18, 16, v161
	v_and_b32_e32 v19, 0xffff0000, v161
	v_lshlrev_b32_e32 v20, 16, v162
	v_and_b32_e32 v21, 0xffff0000, v162
	v_lshlrev_b32_e32 v22, 16, v163
	v_and_b32_e32 v23, 0xffff0000, v163
	v_pk_mul_f32 v[16:17], v[64:65], v[16:17] op_sel_hi:[0,1]
	v_pk_mul_f32 v[18:19], v[64:65], v[18:19] op_sel_hi:[0,1]
	v_pk_mul_f32 v[20:21], v[64:65], v[20:21] op_sel_hi:[0,1]
	v_pk_mul_f32 v[22:23], v[64:65], v[22:23] op_sel_hi:[0,1]
	v_pk_mul_f32 v[32:33], v[88:89], v[16:17]
	v_pk_mul_f32 v[34:35], v[90:91], v[18:19]
	v_pk_mul_f32 v[36:37], v[92:93], v[20:21]
	v_pk_mul_f32 v[38:39], v[94:95], v[22:23]
	global_store_dwordx4 v[56:57], v[32:35], off
	global_store_dwordx4 v[56:57], v[36:39], off offset:16
	v_lshlrev_b32_e32 v16, 16, v164
	v_and_b32_e32 v17, 0xffff0000, v164
	v_lshlrev_b32_e32 v18, 16, v165
	v_and_b32_e32 v19, 0xffff0000, v165
	v_lshlrev_b32_e32 v20, 16, v166
	v_and_b32_e32 v21, 0xffff0000, v166
	v_lshlrev_b32_e32 v22, 16, v167
	v_and_b32_e32 v23, 0xffff0000, v167
	v_pk_mul_f32 v[16:17], v[64:65], v[16:17] op_sel_hi:[0,1]
	v_pk_mul_f32 v[18:19], v[64:65], v[18:19] op_sel_hi:[0,1]
	v_pk_mul_f32 v[20:21], v[64:65], v[20:21] op_sel_hi:[0,1]
	v_pk_mul_f32 v[22:23], v[64:65], v[22:23] op_sel_hi:[0,1]
	v_pk_mul_f32 v[40:41], v[96:97], v[16:17]
	v_pk_mul_f32 v[42:43], v[98:99], v[18:19]
	v_pk_mul_f32 v[44:45], v[100:101], v[20:21]
	v_pk_mul_f32 v[46:47], v[102:103], v[22:23]
	global_store_dwordx4 v[56:57], v[40:43], off offset:2048
	global_store_dwordx4 v[56:57], v[44:47], off offset:2064
	v_lshlrev_b32_e32 v16, 16, v168
	v_and_b32_e32 v17, 0xffff0000, v168
	v_lshlrev_b32_e32 v18, 16, v169
	v_and_b32_e32 v19, 0xffff0000, v169
	v_lshlrev_b32_e32 v20, 16, v170
	v_and_b32_e32 v21, 0xffff0000, v170
	v_lshlrev_b32_e32 v22, 16, v171
	v_and_b32_e32 v23, 0xffff0000, v171
	v_pk_mul_f32 v[16:17], v[66:67], v[16:17] op_sel_hi:[0,1]
	v_pk_mul_f32 v[18:19], v[66:67], v[18:19] op_sel_hi:[0,1]
	v_pk_mul_f32 v[20:21], v[66:67], v[20:21] op_sel_hi:[0,1]
	v_pk_mul_f32 v[22:23], v[66:67], v[22:23] op_sel_hi:[0,1]
	v_pk_mul_f32 v[32:33], v[88:89], v[16:17]
	v_pk_mul_f32 v[34:35], v[90:91], v[18:19]
	v_pk_mul_f32 v[36:37], v[92:93], v[20:21]
	v_pk_mul_f32 v[38:39], v[94:95], v[22:23]
	global_store_dwordx4 v[58:59], v[32:35], off
	global_store_dwordx4 v[58:59], v[36:39], off offset:16
	v_lshlrev_b32_e32 v16, 16, v172
	v_and_b32_e32 v17, 0xffff0000, v172
	v_lshlrev_b32_e32 v18, 16, v173
	v_and_b32_e32 v19, 0xffff0000, v173
	v_lshlrev_b32_e32 v20, 16, v174
	v_and_b32_e32 v21, 0xffff0000, v174
	v_lshlrev_b32_e32 v22, 16, v175
	v_and_b32_e32 v23, 0xffff0000, v175
	v_pk_mul_f32 v[16:17], v[66:67], v[16:17] op_sel_hi:[0,1]
	v_pk_mul_f32 v[18:19], v[66:67], v[18:19] op_sel_hi:[0,1]
	v_pk_mul_f32 v[20:21], v[66:67], v[20:21] op_sel_hi:[0,1]
	v_pk_mul_f32 v[22:23], v[66:67], v[22:23] op_sel_hi:[0,1]
	v_pk_mul_f32 v[40:41], v[96:97], v[16:17]
	v_pk_mul_f32 v[42:43], v[98:99], v[18:19]
	v_pk_mul_f32 v[44:45], v[100:101], v[20:21]
	v_pk_mul_f32 v[46:47], v[102:103], v[22:23]
	global_store_dwordx4 v[58:59], v[40:43], off offset:2048
	global_store_dwordx4 v[58:59], v[44:47], off offset:2064
	v_lshl_add_u64 v[50:51], v[50:51], 0, s[14:15]
	s_cmp_lt_i32 s6, 0x18000
	s_cbranch_scc1 .Lp8_top
